# speedup vs baseline: 1.0020x; 1.0008x over previous
; DEV void phase_norm(const Params& p, int l, int which, int bid, int nb, float* sm) {
;     ...
;     for (int r = bid * 4 + wid; r < MROWS; r += rstep) {
;         float4 cx[4];
; #pragma unroll
;         for (int i = 0; i < 4; ++i) cx[i] = nx[i];
;         {
;             const int rn = r + rstep;
;             if (rn < MROWS) {
;                 const bool pendn = rn >= SEQ && (which == 1 || l == 1);
;                 const float* xn = (which == 0 || (pendn && l == 0)) ? xrow(p, l, rn) : p.out + (size_t)rn * 1024;
; #pragma unroll
;                 for (int i = 0; i < 4; ++i) nx[i] = *(const float4*)(xn + i * 256 + lane * 4);
;             }
;         }
;         const int mi = mod_index(r);
;         if (mi != cur) {
;             cur = mi;
;             const float* md = p.mod() + (size_t)(l * 9 + mi) * 6144 + (which ? 3072 : 0);
; #pragma unroll
;             for (int i = 0; i < 4; ++i) {
;                 const int k = i * 256 + lane * 4;
;                 const float4 sh = *(const float4*)(md + k), s = *(const float4*)(md + 1024 + k), gg = *(const float4*)(g + k);
;                 scl[i * 4 + 0] = gg.x * (1.f + s.x); scl[i * 4 + 1] = gg.y * (1.f + s.y); scl[i * 4 + 2] = gg.z * (1.f + s.z); scl[i * 4 + 3] = gg.w * (1.f + s.w);
;                 sft[i * 4 + 0] = sh.x; sft[i * 4 + 1] = sh.y; sft[i * 4 + 2] = sh.z; sft[i * 4 + 3] = sh.w;
;             }
;         }
;         const bool pend = r >= SEQ && (which == 1 || l == 1);
;         float v[16]; float ss = 0.f;
; #pragma unroll
;         for (int i = 0; i < 4; ++i) {
;             float4 a = cx[i];
;             if (pend) {
;                 const float* pp = (const float*)(p.ws + OFF_part) + (size_t)(r - SEQ) * 1024 + i * 256 + lane * 4;
; #pragma unroll
;                 for (int kq = 0; kq < 4; ++kq) { const float4 q4 = *(const float4*)(pp + (size_t)kq * 128 * 1024); a.x += q4.x; a.y += q4.y; a.z += q4.z; a.w += q4.w; }
;                 *(float4*)(p.out + (size_t)r * 1024 + i * 256 + lane * 4) = a;
;             }
;             v[i * 4] = a.x; v[i * 4 + 1] = a.y; v[i * 4 + 2] = a.z; v[i * 4 + 3] = a.w;
;             ss += a.x * a.x + a.y * a.y + a.z * a.z + a.w * a.w;
;         }
; #pragma unroll
;         for (int o = 32; o >= 1; o >>= 1) ss += __shfl_xor(ss, o);
;         const float rstd = rsqrtf(ss * (1.f / 1024.f) + EPSN);
; #pragma unroll
.LBB0_44:
	s_or_b64 exec, exec, s[14:15]
	v_pk_mul_f32 v[86:87], v[4:5], v[4:5]
	v_pk_mul_f32 v[90:91], v[8:9], v[8:9]
	v_pk_mul_f32 v[88:89], v[6:7], v[6:7]
	v_pk_mul_f32 v[98:99], v[10:11], v[10:11]
	v_add_f32_e32 v40, v91, v90
	v_add_f32_e32 v77, v87, v86
	v_add_f32_e32 v40, v98, v40
	v_add_f32_e32 v77, v88, v77
	v_pk_mul_f32 v[100:101], v[0:1], v[0:1]
	v_mov_b32_e32 v105, v13
	v_mov_b32_e32 v13, v80
	v_add_f32_e32 v40, v99, v40
	v_add_f32_e32 v77, v89, v77
	v_pk_mul_f32 v[102:103], v[2:3], v[2:3]
	v_mov_b32_e32 v104, v81
	v_pk_mul_f32 v[80:81], v[12:13], v[12:13]
	v_add_f32_e32 v40, v77, v40
	v_add_f32_e32 v77, v101, v100
	v_pk_mul_f32 v[106:107], v[104:105], v[104:105]
	v_add_f32_e32 v39, v81, v80
	v_add_f32_e32 v77, v102, v77
	v_add_f32_e32 v39, v106, v39
	v_add_f32_e32 v77, v103, v77
	v_add_f32_e32 v39, v107, v39
	v_add_f32_e32 v40, v40, v77
	v_add_f32_e32 v39, v40, v39
	ds_bpermute_b32 v40, v31, v39
	s_mov_b32 s0, 0x800000
	v_add_u32_e32 v32, s6, v32
	v_lshl_add_u64 v[50:51], v[50:51], 0, s[6:7]
	s_waitcnt lgkmcnt(0)
	v_add_f32_e32 v39, v39, v40
	ds_bpermute_b32 v40, v92, v39
	s_waitcnt lgkmcnt(0)
	v_add_f32_e32 v39, v39, v40
	ds_bpermute_b32 v40, v93, v39
	s_waitcnt lgkmcnt(0)
	v_add_f32_e32 v39, v39, v40
	ds_bpermute_b32 v40, v94, v39
	s_waitcnt lgkmcnt(0)
	v_add_f32_e32 v39, v39, v40
	ds_bpermute_b32 v40, v95, v39
	s_waitcnt lgkmcnt(0)
	v_add_f32_e32 v39, v39, v40
	ds_bpermute_b32 v40, v96, v39
	s_waitcnt lgkmcnt(0)
	v_add_f32_e32 v39, v39, v40
	v_fmamk_f32 v39, v39, 0x3a800000, v189
	v_mul_f32_e32 v40, 0x4b800000, v39
	v_cmp_gt_f32_e32 vcc, s0, v39
	s_movk_i32 s0, 0x407f
	s_nop 0
	v_cndmask_b32_e32 v39, v39, v40, vcc
	v_rsq_f32_e32 v39, v39
	s_nop 0
	v_mul_f32_e32 v40, 0x45800000, v39
	v_cndmask_b32_e32 v40, v39, v40, vcc
	v_pk_mul_f32 v[4:5], v[4:5], v[40:41] op_sel_hi:[1,0]
	v_pk_mul_f32 v[6:7], v[6:7], v[40:41] op_sel_hi:[1,0]
	v_pk_mul_f32 v[0:1], v[0:1], v[40:41] op_sel_hi:[1,0]
	v_pk_mul_f32 v[2:3], v[2:3], v[40:41] op_sel_hi:[1,0]
	v_pk_mul_f32 v[8:9], v[8:9], v[40:41] op_sel_hi:[1,0]
	v_pk_mul_f32 v[10:11], v[10:11], v[40:41] op_sel_hi:[1,0]
	v_pk_fma_f32 v[4:5], v[64:65], v[4:5], v[14:15]
	v_pk_fma_f32 v[6:7], v[60:61], v[6:7], v[16:17]
	v_pk_fma_f32 v[0:1], v[70:71], v[0:1], v[22:23]
	v_pk_fma_f32 v[2:3], v[66:67], v[2:3], v[24:25]
	v_pk_mul_f32 v[12:13], v[12:13], v[40:41] op_sel_hi:[1,0]
	v_pk_mul_f32 v[80:81], v[104:105], v[40:41] op_sel_hi:[1,0]
	v_pk_fma_f32 v[8:9], v[68:69], v[8:9], v[18:19]
	v_pk_fma_f32 v[10:11], v[62:63], v[10:11], v[20:21]
	s_waitcnt vmcnt(0)
	v_pk_fma_f32 v[12:13], v[72:73], v[12:13], v[26:27]
	v_pk_fma_f32 v[80:81], v[84:85], v[80:81], v[28:29]
	v_cvt_pk_bf16_f32 v4, v4, v5
	v_cvt_pk_bf16_f32 v5, v6, v7
	v_cvt_pk_bf16_f32 v0, v0, v1
	v_cvt_pk_bf16_f32 v1, v2, v3
	flat_store_dwordx2 v[58:59], v[4:5]
	v_cvt_pk_bf16_f32 v4, v8, v9
	v_cvt_pk_bf16_f32 v5, v10, v11
	flat_store_dwordx2 v[58:59], v[0:1] offset:2048
	v_cvt_pk_bf16_f32 v0, v12, v13
	v_cvt_pk_bf16_f32 v1, v80, v81
	v_cmp_lt_i32_e32 vcc, s0, v32
	flat_store_dwordx2 v[58:59], v[4:5] offset:1024
	flat_store_dwordx2 v[58:59], v[0:1] offset:3072
	v_lshl_add_u64 v[58:59], v[58:59], 0, s[10:11]
	s_or_b64 s[12:13], vcc, s[12:13]
	v_mov_b32_e32 v80, v121
	v_mov_b32_e32 v81, v122
	v_mov_b64_e32 v[6:7], v[48:49]
	v_mov_b64_e32 v[4:5], v[46:47]
	v_mov_b64_e32 v[10:11], v[44:45]
	v_mov_b64_e32 v[8:9], v[42:43]
	v_mov_b64_e32 v[2:3], v[36:37]
	v_mov_b64_e32 v[0:1], v[34:35]
	v_mov_b32_e32 v12, v120
	v_mov_b32_e32 v13, v123
	s_andn2_b64 exec, exec, s[12:13]
	s_cbranch_execz .LBB0_57
.LBB0_45:
	s_movk_i32 s0, 0x4080
	v_cmp_gt_i32_e32 vcc, s0, v50
	v_lshlrev_b32_e32 v86, 2, v30
	v_mov_b64_e32 v[48:49], v[6:7]
	v_mov_b64_e32 v[46:47], v[4:5]
	v_mov_b64_e32 v[44:45], v[10:11]
	v_mov_b64_e32 v[42:43], v[8:9]
	v_mov_b64_e32 v[36:37], v[2:3]
	v_mov_b64_e32 v[34:35], v[0:1]
	v_mov_b32_e32 v120, v12
	v_mov_b32_e32 v123, v13
	v_mov_b32_e32 v121, v80
	v_mov_b32_e32 v122, v81
	s_and_saveexec_b64 s[0:1], vcc
	s_cbranch_execz .LBB0_47
	s_movk_i32 s14, 0x3fff
	v_cmp_lt_i32_e32 vcc, s14, v50
	v_readlane_b32 s14, v253, 27
	v_readlane_b32 s15, v253, 28
	v_add_u32_e32 v34, 0xffffc000, v50
	s_and_b64 vcc, s[8:9], vcc
	v_mov_b32_e32 v36, s93
	v_mov_b32_e32 v37, s15
	v_cndmask_b32_e64 v35, v51, 0, vcc
	v_cndmask_b32_e32 v34, v50, v34, vcc
	v_cndmask_b32_e32 v37, v36, v37, vcc
	v_mov_b32_e32 v36, s92
	v_mov_b32_e32 v38, s14
	v_cndmask_b32_e32 v36, v36, v38, vcc
	v_lshlrev_b64 v[34:35], 12, v[34:35]
	v_lshl_add_u64 v[34:35], v[36:37], 0, v[34:35]
	v_mov_b32_e32 v87, v33
	v_lshl_add_u64 v[42:43], v[34:35], 0, v[86:87]
	global_load_dwordx4 v[34:37], v[42:43], off offset:2048
	global_load_dwordx4 v[120:123], v[42:43], off offset:3072
	global_load_dwordx4 v[46:49], v[42:43], off
	s_nop 0
	global_load_dwordx4 v[42:45], v[42:43], off offset:1024
	s_nop 0
	s_nop 0
	s_nop 0
